# XCD-local grid barriers for row-panel-local GEMM-to-GEMM dependencies, guarded by a runtime placement check (one-hot XCC mask per blockIdx%8 group) with global-barrier fallback
# speedup vs baseline: 1.0189x; 1.0079x over previous
_Z8mega_fwd6Params:
	s_mov_b64 s[4:5], s[0:1]
	v_writelane_b32 v251, s2, 0
	s_load_dword s2, s[0:1], 0x120
	s_load_dwordx4 s[8:11], s[0:1], 0x110
	s_add_u32 s6, s4, 0x118
	s_load_dwordx2 s[0:1], s[0:1], 0xc8
	v_and_b32_e32 v199, 0x3ff, v0
	v_cmp_gt_u32_e32 vcc, 2, v199
	s_waitcnt lgkmcnt(0)
	v_writelane_b32 v251, s8, 1
	s_nop 1
	v_writelane_b32 v251, s9, 2
	v_writelane_b32 v251, s10, 3
	v_writelane_b32 v251, s11, 4
	v_writelane_b32 v251, s0, 5
	s_nop 1
	v_writelane_b32 v251, s1, 6
	v_writelane_b32 v251, s4, 7
	s_addc_u32 s7, s5, 0
	s_nop 0
	v_writelane_b32 v251, s5, 8
	s_and_saveexec_b64 s[0:1], vcc
	v_lshl_add_u32 v1, v199, 2, 0
	v_add_u32_e32 v1, 0x20000, v1
	v_mov_b32_e32 v2, 0
	ds_write_b32 v1, v2
	s_or_b64 exec, exec, s[0:1]
	v_readlane_b32 s12, v251, 1
	v_readlane_b32 s13, v251, 2
	s_cmp_eq_u32 s12, 0
	s_cselect_b64 s[4:5], -1, 0
	s_cmpk_gt_i32 s13, 0x3e7
	s_cselect_b64 s[8:9], -1, 0
	s_and_b64 s[4:5], s[4:5], s[8:9]
	v_readlane_b32 s8, v251, 7
	v_readlane_b32 s9, v251, 8
	s_load_dwordx2 s[8:9], s[8:9], 0xc8
	v_cndmask_b32_e64 v1, 0, 1, s[4:5]
	s_mov_b32 s0, 0
	v_cmp_ne_u32_e64 s[78:79], 1, v1
	v_mov_b32_e32 v1, s13
	s_waitcnt lgkmcnt(0)
	s_add_u32 s48, s8, 0x16900000
	s_addc_u32 s49, s9, 0
	s_andn2_b64 vcc, exec, s[4:5]
	v_cmp_eq_u32_e64 s[4:5], 0, v199
	v_readlane_b32 s14, v251, 3
	v_readlane_b32 s15, v251, 4
	s_barrier
	s_cbranch_vccnz .LBB0_8
	v_readlane_b32 s8, v251, 1
	s_getreg_b32 s0, hwreg(HW_REG_XCC_ID, 0, 4)
	v_readlane_b32 s9, v251, 2
	s_and_b32 s0, s0, 15
	v_readlane_b32 s10, v251, 3
	v_mov_b32_e32 v1, s9
	v_readlane_b32 s11, v251, 4
	s_and_saveexec_b64 s[8:9], s[4:5]
	s_cbranch_execz .LBB0_7
	s_mov_b64 s[10:11], exec
	v_mbcnt_lo_u32_b32 v1, s10, 0
	v_readlane_b32 s12, v251, 1
	v_mbcnt_hi_u32_b32 v1, s11, v1
	v_readlane_b32 s13, v251, 2
	v_cmp_eq_u32_e32 vcc, 0, v1
	v_readlane_b32 s14, v251, 3
	v_mov_b32_e32 v1, s13
	v_readlane_b32 s15, v251, 4
	s_and_saveexec_b64 s[4:5], vcc
	s_cbranch_execz .LBB0_6
	v_readlane_b32 s1, v251, 0
	s_and_b32 s1, s1, 7
	s_lshl_b32 s1, s1, 2
	s_lshl_b32 s3, 1, s0
	v_mov_b32_e32 v1, s1
	v_mov_b32_e32 v2, s3
	global_atomic_or v2, v1, v2, s[48:49] offset:32 sc0
	s_waitcnt vmcnt(0)
	s_lshl_b32 s1, s0, 8
	s_bcnt1_i32_b64 s3, s[10:11]
	v_mov_b32_e32 v1, s1
	v_mov_b32_e32 v2, s3
	global_atomic_add v1, v2, s[48:49] offset:1024
	v_readlane_b32 s10, v251, 7
	v_readlane_b32 s11, v251, 8
	s_load_dword s1, s[10:11], 0x114
	s_waitcnt lgkmcnt(0)
	v_mov_b32_e32 v1, s1

.LBB0_87:
	s_cmp_eq_u32 s0, 0
	s_cselect_b64 vcc, -1, 0
	s_cmp_eq_u32 s0, 1
	v_cndmask_b32_e32 v16, 0, v15, vcc
	s_cselect_b64 vcc, -1, 0
	s_cmp_eq_u32 s0, 2
	v_cndmask_b32_e32 v16, v16, v0, vcc
	s_cselect_b64 vcc, -1, 0
	s_cmp_eq_u32 s0, 3
	v_cndmask_b32_e32 v16, v16, v1, vcc
	s_cselect_b64 vcc, -1, 0
	s_cmp_eq_u32 s0, 4
	v_cndmask_b32_e32 v16, v16, v2, vcc
	s_cselect_b64 vcc, -1, 0
	s_cmp_eq_u32 s0, 5
	v_cndmask_b32_e32 v16, v16, v3, vcc
	s_cselect_b64 vcc, -1, 0
	s_cmp_eq_u32 s0, 6
	v_cndmask_b32_e32 v16, v16, v4, vcc
	s_cselect_b64 vcc, -1, 0
	s_cmp_eq_u32 s0, 7
	v_cndmask_b32_e32 v16, v16, v5, vcc
	s_cselect_b64 vcc, -1, 0
	s_cmp_eq_u32 s0, 8
	v_cndmask_b32_e32 v16, v16, v6, vcc
	s_cselect_b64 vcc, -1, 0
	s_cmp_eq_u32 s0, 9
	v_cndmask_b32_e32 v16, v16, v7, vcc
	s_cselect_b64 vcc, -1, 0
	s_cmp_eq_u32 s0, 10
	v_cndmask_b32_e32 v16, v16, v8, vcc
	s_cselect_b64 vcc, -1, 0
	s_cmp_eq_u32 s0, 11
	v_cndmask_b32_e32 v16, v16, v9, vcc
	s_cselect_b64 vcc, -1, 0
	s_cmp_eq_u32 s0, 12
	v_cndmask_b32_e32 v16, v16, v10, vcc
	s_cselect_b64 vcc, -1, 0
	s_cmp_eq_u32 s0, 13
	v_cndmask_b32_e32 v16, v16, v11, vcc
	s_cselect_b64 vcc, -1, 0
	s_cmp_eq_u32 s0, 14
	v_cndmask_b32_e32 v16, v16, v12, vcc
	s_cselect_b64 vcc, -1, 0
	s_cmp_eq_u32 s0, 15
	v_cndmask_b32_e32 v16, v16, v13, vcc
	s_cselect_b64 vcc, -1, 0
	v_cndmask_b32_e32 v16, v16, v14, vcc
	v_cmp_ne_u32_e32 vcc, 0, v15
	s_add_i32 s1, 0, 0x20000
	s_nop 0
	v_cndmask_b32_e64 v15, 0, 1, vcc
	v_cmp_ne_u32_e32 vcc, 0, v0
	s_nop 1
	v_addc_co_u32_e32 v0, vcc, 0, v15, vcc
	v_cmp_ne_u32_e32 vcc, 0, v1
	s_nop 1
	v_cndmask_b32_e64 v1, 0, 1, vcc
	v_cmp_ne_u32_e32 vcc, 0, v2
	v_max_u32_e32 v2, 1, v16
	s_nop 0
	v_addc_co_u32_e32 v0, vcc, v0, v1, vcc
	v_cmp_ne_u32_e32 vcc, 0, v3
	s_nop 1
	v_cndmask_b32_e64 v1, 0, 1, vcc
	v_cmp_ne_u32_e32 vcc, 0, v4
	s_nop 1
	v_addc_co_u32_e32 v0, vcc, v0, v1, vcc
	v_cmp_ne_u32_e32 vcc, 0, v5
	s_nop 1
	v_cndmask_b32_e64 v1, 0, 1, vcc
	v_cmp_ne_u32_e32 vcc, 0, v6
	s_nop 1
	v_addc_co_u32_e32 v0, vcc, v0, v1, vcc
	v_cmp_ne_u32_e32 vcc, 0, v7
	s_nop 1
	v_cndmask_b32_e64 v1, 0, 1, vcc
	v_cmp_ne_u32_e32 vcc, 0, v8
	s_nop 1
	v_addc_co_u32_e32 v0, vcc, v0, v1, vcc
	v_cmp_ne_u32_e32 vcc, 0, v9
	s_nop 1
	v_cndmask_b32_e64 v1, 0, 1, vcc
	v_cmp_ne_u32_e32 vcc, 0, v10
	s_nop 1
	v_addc_co_u32_e32 v0, vcc, v0, v1, vcc
	v_cmp_ne_u32_e32 vcc, 0, v11
	s_nop 1
	v_cndmask_b32_e64 v1, 0, 1, vcc
	v_cmp_ne_u32_e32 vcc, 0, v12
	s_nop 1
	v_addc_co_u32_e32 v0, vcc, v0, v1, vcc
	v_cmp_ne_u32_e32 vcc, 0, v13
	s_nop 1
	v_cndmask_b32_e64 v1, 0, 1, vcc
	v_cmp_ne_u32_e32 vcc, 0, v14
	s_nop 1
	v_addc_co_u32_e32 v0, vcc, v0, v1, vcc
	v_mov_b32_e32 v1, s1
	s_add_i32 s1, 0, 0x20004
	v_max_u32_e32 v0, 1, v0
	ds_write_b32 v1, v2
	v_mov_b32_e32 v1, s1
	ds_write_b32 v1, v0
	v_mov_b32_e32 v1, 0
	global_load_dword v3, v1, s[48:49] offset:32 sc1
	global_load_dword v4, v1, s[48:49] offset:36 sc1
	global_load_dword v5, v1, s[48:49] offset:40 sc1
	global_load_dword v6, v1, s[48:49] offset:44 sc1
	global_load_dword v7, v1, s[48:49] offset:48 sc1
	global_load_dword v8, v1, s[48:49] offset:52 sc1
	global_load_dword v9, v1, s[48:49] offset:56 sc1
	global_load_dword v10, v1, s[48:49] offset:60 sc1
	s_waitcnt vmcnt(0)
	v_or3_b32 v11, v3, v4, v5
	v_bcnt_u32_b32 v12, v3, 0
	v_or3_b32 v11, v11, v6, v7
	v_bcnt_u32_b32 v12, v4, v12
	v_or3_b32 v11, v11, v8, v9
	v_bcnt_u32_b32 v12, v5, v12
	v_or_b32_e32 v11, v11, v10
	v_bcnt_u32_b32 v12, v6, v12
	v_bcnt_u32_b32 v12, v7, v12
	v_bcnt_u32_b32 v12, v8, v12
	v_bcnt_u32_b32 v12, v9, v12
	v_bcnt_u32_b32 v12, v10, v12
	s_nop 1
	v_readfirstlane_b32 s1, v11
	v_readfirstlane_b32 s3, v12
	v_readlane_b32 s6, v251, 3
	s_cmpk_eq_u32 s1, 0xff
	s_cselect_b32 s1, 1, 0
	s_cmp_eq_u32 s3, 8
	s_cselect_b32 s3, 1, 0
	s_and_b32 s1, s1, s3
	s_cmpk_eq_u32 s6, 0x100
	s_cselect_b32 s3, 1, 0
	s_and_b32 s1, s1, s3
	v_writelane_b32 v248, s1, 40

.Lloc_d:
	v_readlane_b32 s2, v252, 49
	v_readlane_b32 s3, v252, 50
	s_waitcnt vmcnt(0)
	buffer_inv sc1
	s_nop 2
	global_atomic_add v197, v223, s[2:3]
	s_waitcnt vmcnt(0)

.LBB0_599:
	s_andn2_saveexec_b64 s[2:3], s[8:9]
	s_cbranch_execz .LBB0_617
	s_mov_b64 s[8:9], exec
	v_readlane_b32 s2, v248, 40
	s_cmp_eq_u32 s2, 0
	s_cbranch_scc1 .Lglob_a
	s_branch .Lloc_a
.Lglob_a:
	buffer_wbl2 sc1
	s_waitcnt lgkmcnt(0)
	s_waitcnt vmcnt(0)
	v_mbcnt_lo_u32_b32 v1, s8, 0
	v_mbcnt_hi_u32_b32 v1, s9, v1
	v_cmp_eq_u32_e32 vcc, 0, v1
	s_and_saveexec_b64 s[12:13], vcc
	s_cbranch_execz .LBB0_602
	s_bcnt1_i32_b64 s1, s[8:9]
	v_readlane_b32 s2, v252, 51
	v_mov_b32_e32 v2, s1
	v_readlane_b32 s3, v252, 52
	s_nop 4
	global_atomic_add v2, v197, v2, s[2:3] sc0

.LBB0_653:
	s_andn2_saveexec_b64 s[2:3], s[8:9]
	s_cbranch_execz .LBB0_671
	s_mov_b64 s[8:9], exec
	v_readlane_b32 s2, v248, 40
	s_cmp_eq_u32 s2, 0
	s_cbranch_scc1 .Lglob_b
	v_readlane_b32 s2, v249, 53
	s_cmp_lg_u32 s2, 1
	s_cbranch_scc1 .Lloc_b

.LBB0_909:
	s_andn2_saveexec_b64 s[2:3], s[8:9]
	s_cbranch_execz .LBB0_125
	v_readlane_b32 s2, v248, 40
	s_cmp_eq_u32 s2, 0
	s_cbranch_scc1 .Lglob_d
	v_readlane_b32 s2, v249, 53
	s_cmp_eq_u32 s2, 1
	s_cbranch_scc1 .Lloc_d
	s_cmp_lg_u32 s2, 0
	s_cbranch_scc1 .Lglob_d
	v_readlane_b32 s2, v249, 21
	s_cmp_gt_u32 s2, 1
	s_cbranch_scc1 .Lloc_d
.Lglob_d:
	s_mov_b64 s[8:9], exec
	buffer_wbl2 sc1
	s_waitcnt lgkmcnt(0)
	s_waitcnt vmcnt(0)
	v_mbcnt_lo_u32_b32 v1, s8, 0
	v_mbcnt_hi_u32_b32 v1, s9, v1
	v_cmp_eq_u32_e32 vcc, 0, v1
	s_and_saveexec_b64 s[12:13], vcc
	s_cbranch_execz .LBB0_912
	s_bcnt1_i32_b64 s2, s[8:9]
	v_mov_b32_e32 v2, s2
	v_readlane_b32 s2, v252, 51
	v_readlane_b32 s3, v252, 52
	s_nop 4
	global_atomic_add v2, v197, v2, s[2:3] sc0
